# r48 + in-proj GEMM code shifted by 36 bytes (loop label at 16 mod 64) with compensating unreachable padding after it
# baseline (speedup 1.0000x reference)
.LBB0_95:
	v_readlane_b32 s4, v252, 51
	s_mov_b64 s[2:3], 0x80
	v_readlane_b32 s5, v252, 52
	s_add_i32 m0, s22, 0x18000
	v_lshl_add_u64 v[2:3], v[2:3], 0, s[2:3]
	v_lshl_add_u64 v[10:11], s[4:5], 0, v[132:133]
	s_lshl_b32 s1, s1, 5
	s_waitcnt vmcnt(4)
	s_barrier
	global_load_lds_dwordx4 v[2:3], off
	v_lshl_add_u64 v[2:3], v[4:5], 0, s[2:3]
	s_add_i32 m0, s22, 0x1a000
	s_add_i32 s27, s22, 0x8000
	v_lshl_add_u64 v[12:13], s[4:5], 0, v[130:131]
	s_and_b32 s26, s1, 0x60
	global_load_lds_dwordx4 v[2:3], off
	v_lshl_add_u64 v[2:3], v[10:11], 0, s[2:3]
	s_mov_b32 m0, s27
	s_add_i32 s28, s22, 0xa000
	global_load_lds_dwordx4 v[2:3], off
	v_lshl_add_u64 v[2:3], v[12:13], 0, s[2:3]
	s_add_u32 s2, s6, 0x40080
	s_mov_b32 m0, s28
	s_addc_u32 s3, s7, 0
	global_load_lds_dwordx4 v[2:3], off
	s_add_i32 m0, s22, 0x1c000
	v_lshl_add_u64 v[2:3], s[2:3], 0, v[132:133]
	global_load_lds_dwordx4 v[2:3], off
	v_lshl_add_u64 v[2:3], s[2:3], 0, v[130:131]
	s_add_i32 m0, s22, 0x1e000
	v_lshrrev_b32_e32 v5, 1, v6
	global_load_lds_dwordx4 v[2:3], off
	v_and_b32_e32 v2, 15, v6
	v_and_b32_e32 v3, 3, v1
	v_bfe_u32 v9, v6, 1, 3
	v_lshl_or_b32 v1, s0, 6, v2
	v_bitop3_b32 v5, v5, v3, 7 bitop3:0x6c
	v_bitop3_b32 v9, v3, v9, 4 bitop3:0x36
	v_or_b32_e32 v2, s26, v2
	v_lshlrev_b32_e32 v4, 7, v1
	v_lshlrev_b32_e32 v5, 4, v5
	v_lshlrev_b32_e32 v9, 4, v9
	v_lshlrev_b32_e32 v2, 7, v2
	v_lshlrev_b32_e32 v134, 3, v3
	v_and_b32_e32 v3, 7, v8
	v_or_b32_e32 v10, v4, v5
	v_or_b32_e32 v168, v2, v5
	v_or_b32_e32 v169, v2, v9
	v_lshlrev_b32_e32 v2, 8, v6
	v_lshlrev_b32_e32 v5, 4, v3
	s_movk_i32 s0, 0xf800
	v_and_or_b32 v2, v2, s0, v5
	v_mov_b32_e32 v3, v0
	s_mov_b64 s[2:3], 0x40080
	v_lshl_add_u64 v[136:137], v[2:3], 0, s[2:3]
	v_lshlrev_b32_e32 v2, 1, v7
	s_waitcnt vmcnt(6)
	v_and_or_b32 v2, v2, s0, v5
	v_readlane_b32 s0, v253, 55
	v_or_b32_e32 v4, v9, v4
	v_or_b32_e32 v170, 16, v1
	v_add_u32_e32 v181, s0, v168
	v_add_u32_e32 v197, s0, v169
	v_readlane_b32 s0, v252, 49
	v_or_b32_e32 v171, 32, v1
	v_or_b32_e32 v172, 48, v1
	v_mov_b32_e32 v135, v0
	v_lshl_add_u64 v[138:139], v[2:3], 0, s[2:3]
	s_mov_b32 s29, 0
	v_add_u32_e32 v173, s8, v168
	v_add_u32_e32 v174, s8, v169
	v_add_u32_e32 v175, 0, v10
	v_add_u32_e32 v176, 0, v4
	v_add_u32_e32 v177, s85, v168
	v_add_u32_e32 v178, s85, v169
	v_add_u32_e32 v179, s80, v168
	v_add_u32_e32 v180, s80, v169
	v_readlane_b32 s30, v252, 46
	s_mov_b32 s31, s0
	s_barrier
	v_readlane_b32 s1, v252, 50
	s_branch .LBB0_97
	s_nop 0
	s_nop 0
	s_nop 0
	s_nop 0
	s_nop 0
	s_nop 0
	s_nop 0
	s_nop 0
	s_nop 0

.LBB0_183:
	s_andn2_saveexec_b64 s[4:5], s[4:5]
	s_cbranch_execz .LBB0_96
	s_ashr_i32 s15, s14, 31
	v_cvt_pk_bf16_f32 v6, v6, v7
	v_cvt_pk_bf16_f32 v7, v8, v9
	v_cvt_pk_bf16_f32 v8, v2, v3
	v_lshl_add_u64 v[2:3], s[14:15], 0, v[134:135]
	v_cvt_pk_bf16_f32 v9, v4, v5
	v_lshl_add_u64 v[2:3], v[2:3], 1, v[20:21]
	global_store_dwordx4 v[2:3], v[6:9], off offset:256
	s_branch .LBB0_96
	s_nop 0
	s_nop 0
	s_nop 0
	s_nop 0
	s_nop 0
	s_nop 0
	s_nop 0
